# attention fast tile: serial sum-reduce chain before the bump-check branch shortened (6 v_mov + 3 pk_add + 2 s_nop -> 4 v_add + 1 pk_add), 3 sites, on top of v030
# speedup vs baseline: 1.0141x; 1.0141x over previous
; #define LAS __attribute__((address_space(3)))
; DI float fast_exp2(float x) { return __builtin_amdgcn_exp2f(x); }
; #define MFMA16(a, b, c) __builtin_amdgcn_mfma_f32_16x16x32_bf16((a), (b), (c), 0, 0, 0)
; DI void at_qk(f32x4 (&s1)[4], f32x4 (&s2)[4], const LAS unsigned char* buf, const bf16x8 q1, const bf16x8 q2, const f32x4 (&ci)[4], int hh, int fr, int fq) {
; #pragma unroll
;     for (int k4 = 0; k4 < 4; ++k4) { const LAS unsigned char* kr = buf + AT_K + (16 * k4 + fr) * 272 + hh * 128 + fq * 16;
;         s1[k4] = MFMA16(ld8l(kr), q1, ci[k4]); s2[k4] = MFMA16(ld8l(kr + 64), q2, ci[k4]); }
; }
; DI void at_exp(f32x4 (&s1)[4], f32x4 (&s2)[4], float& ps1, float& ps2) {
;     f32x4 a1 = (f32x4){0.f, 0.f, 0.f, 0.f}, a2 = a1;
; #pragma unroll
;     for (int k4 = 0; k4 < 4; ++k4) {
; #pragma unroll
;         for (int j = 0; j < 4; ++j) { s1[k4][j] = fast_exp2(s1[k4][j]); s2[k4][j] = fast_exp2(s2[k4][j]); }
;         a1 = a1 + s1[k4]; a2 = a2 + s2[k4]; }
;     ps1 = (a1[0] + a1[1]) + (a1[2] + a1[3]); ps2 = (a2[0] + a2[1]) + (a2[2] + a2[3]);
; }
; template <int VAR>
; DI void attn_tile(AtState& S, const LAS unsigned char* buf, const bf16x8 q1, const bf16x8 q2, int kt, bool diag, int qpos0, int qpos_l, float slope2, float adv, float decay, int hh, int fr, int fq) {
;     ...
;         asm volatile("; attention: fast tile" ::: "memory");
;         at_qk(s1, s2, buf, q1, q2, S.cinit, hh, fr, fq);
;         S.ref += adv;
;         at_exp(s1, s2, ps1, ps2);
;         if (__any(!(ps1 + ps2 < 0x1p60f))) {
;             asm volatile("; attention: bump" ::: "memory");
;             at_qk(s1, s2, buf, q1, q2, S.cinit, hh, fr, fq);
;             float lm = -1e30f;
; #pragma unroll
;             for (int k4 = 0; k4 < 4; ++k4)
; #pragma unroll
;                 for (int j = 0; j < 4; ++j) lm = fmaxf(lm, fmaxf(s1[k4][j], s2[k4][j]));
;             lm = fmaxf(lm, __shfl_xor(lm, 16)); lm = fmaxf(lm, __shfl_xor(lm, 32));
.LBB0_1376:
	s_add_i32 s27, s26, -1
	s_min_i32 s14, s27, s25
	s_ashr_i32 s15, s14, 31
	s_add_i32 s28, s22, s26
	s_lshl_b64 s[14:15], s[14:15], 18
	s_add_u32 s14, s0, s14
	s_addc_u32 s15, s1, s15
	global_load_dwordx4 v[28:31], v144, s[14:15] offset:1024
	global_load_dwordx4 v[32:35], v144, s[14:15] offset:1536
	global_load_dwordx4 v[36:39], v146, s[14:15] offset:1024
	global_load_dwordx4 v[40:43], v146, s[14:15] offset:1536
	s_cmpk_eq_i32 s28, 0x42
	s_cselect_b64 s[16:17], -1, 0
	s_cmp_eq_u32 s26, 3
	s_cselect_b64 s[14:15], -1, 0
	s_or_b64 s[18:19], s[14:15], s[16:17]
	s_andn2_b64 vcc, exec, s[18:19]
	s_mov_b64 s[18:19], -1
	s_cbranch_vccz .LBB0_1381
	ds_read_b128 v[76:79], v213
	ds_read_b128 v[80:83], v213 offset:64
	ds_read_b128 v[96:99], v213 offset:4352
	ds_read_b128 v[104:107], v213 offset:4416
	ds_read_b128 v[108:111], v213 offset:8704
	ds_read_b128 v[112:115], v213 offset:8768
	ds_read_b128 v[116:119], v213 offset:13056
	ds_read_b128 v[120:123], v213 offset:13120
	s_waitcnt lgkmcnt(7)
	v_mfma_f32_16x16x32_bf16 v[76:79], v[76:79], v[4:7], v[44:47]
	v_add_f32_e32 v215, v205, v214
	s_waitcnt lgkmcnt(6)
	v_mfma_f32_16x16x32_bf16 v[80:83], v[80:83], v[8:11], v[44:47]
	s_waitcnt lgkmcnt(5)
	v_mfma_f32_16x16x32_bf16 v[96:99], v[96:99], v[4:7], v[48:51]
	s_nop 2
	v_exp_f32_e32 v164, v76
	v_exp_f32_e32 v165, v77
	v_exp_f32_e32 v168, v78
	s_waitcnt lgkmcnt(4)
	v_mfma_f32_16x16x32_bf16 v[104:107], v[104:107], v[8:11], v[48:51]
	v_exp_f32_e32 v169, v79
	v_exp_f32_e32 v162, v80
	v_exp_f32_e32 v163, v81
	s_waitcnt lgkmcnt(3)
	v_mfma_f32_16x16x32_bf16 v[108:111], v[108:111], v[4:7], v[52:55]
	v_exp_f32_e32 v166, v82
	v_exp_f32_e32 v167, v83
	v_exp_f32_e32 v172, v96
	s_waitcnt lgkmcnt(2)
	v_mfma_f32_16x16x32_bf16 v[76:79], v[112:115], v[8:11], v[52:55]
	v_exp_f32_e32 v170, v104
	v_exp_f32_e32 v173, v97
	v_exp_f32_e32 v176, v98
	s_waitcnt lgkmcnt(1)
	v_mfma_f32_16x16x32_bf16 v[80:83], v[116:119], v[4:7], v[56:59]
	v_exp_f32_e32 v177, v99
	v_exp_f32_e32 v174, v106
	v_exp_f32_e32 v175, v107
	s_waitcnt lgkmcnt(0)
	v_mfma_f32_16x16x32_bf16 v[112:115], v[120:123], v[8:11], v[56:59]
	v_exp_f32_e32 v171, v105
	v_exp_f32_e32 v180, v108
	v_exp_f32_e32 v178, v76
	v_exp_f32_e32 v181, v109
	v_exp_f32_e32 v179, v77
	v_exp_f32_e32 v184, v110
	v_exp_f32_e32 v185, v111
	v_exp_f32_e32 v182, v78
	v_exp_f32_e32 v183, v79
	v_exp_f32_e32 v188, v80
	v_exp_f32_e32 v186, v112
	v_exp_f32_e32 v189, v81
	v_exp_f32_e32 v192, v82
	v_exp_f32_e32 v193, v83
	v_exp_f32_e32 v190, v114
	v_exp_f32_e32 v191, v115
	v_exp_f32_e32 v187, v113
	v_pk_add_f32 v[96:97], v[168:169], v[176:177]
	v_pk_add_f32 v[98:99], v[164:165], v[172:173]
	v_pk_add_f32 v[104:105], v[166:167], v[174:175]
	v_pk_add_f32 v[106:107], v[162:163], v[170:171]
	v_pk_add_f32 v[76:77], v[98:99], v[180:181]
	v_pk_add_f32 v[78:79], v[96:97], v[184:185]
	v_pk_add_f32 v[96:97], v[106:107], v[178:179]
	v_pk_add_f32 v[98:99], v[104:105], v[182:183]
	v_pk_add_f32 v[78:79], v[78:79], v[192:193]
	v_pk_add_f32 v[76:77], v[76:77], v[188:189]
	v_pk_add_f32 v[80:81], v[98:99], v[190:191]
	v_pk_add_f32 v[82:83], v[96:97], v[186:187]
	v_add_f32_e32 v96, v82, v83
	v_add_f32_e32 v97, v76, v77
	v_add_f32_e32 v82, v80, v81
	v_add_f32_e32 v83, v78, v79
	v_pk_add_f32 v[194:195], v[96:97], v[82:83]
	v_add_f32_e32 v3, v195, v194
	v_cmp_ngt_f32_e32 vcc, s65, v3
	s_cbranch_vccz .LBB0_1394
	ds_read_b128 v[76:79], v213
	ds_read_b128 v[80:83], v213 offset:64
	ds_read_b128 v[96:99], v213 offset:4352
	ds_read_b128 v[104:107], v213 offset:4416
	ds_read_b128 v[108:111], v213 offset:8704
	ds_read_b128 v[112:115], v213 offset:8768
	ds_read_b128 v[116:119], v213 offset:13056
	ds_read_b128 v[120:123], v213 offset:13120
	s_waitcnt lgkmcnt(7)
	v_mfma_f32_16x16x32_bf16 v[76:79], v[76:79], v[4:7], v[44:47]
	s_waitcnt lgkmcnt(6)
	v_mfma_f32_16x16x32_bf16 v[80:83], v[80:83], v[8:11], v[44:47]
	s_waitcnt lgkmcnt(5)
	v_mfma_f32_16x16x32_bf16 v[96:99], v[96:99], v[4:7], v[48:51]
	s_waitcnt lgkmcnt(4)
	v_mfma_f32_16x16x32_bf16 v[104:107], v[104:107], v[8:11], v[48:51]
	s_waitcnt lgkmcnt(3)
	v_mfma_f32_16x16x32_bf16 v[108:111], v[108:111], v[4:7], v[52:55]
	s_waitcnt lgkmcnt(2)
	v_mfma_f32_16x16x32_bf16 v[112:115], v[112:115], v[8:11], v[52:55]
	s_waitcnt lgkmcnt(1)
	v_mfma_f32_16x16x32_bf16 v[116:119], v[116:119], v[4:7], v[56:59]
	s_waitcnt lgkmcnt(0)
	v_mfma_f32_16x16x32_bf16 v[120:123], v[120:123], v[8:11], v[56:59]
	v_max3_f32 v3, v76, v80, s60
	v_max3_f32 v3, v3, v77, v81
	v_max3_f32 v3, v3, v78, v82
	v_max3_f32 v3, v3, v79, v83
	v_max3_f32 v3, v3, v96, v104
	v_max3_f32 v3, v3, v97, v105
	v_max3_f32 v3, v3, v98, v106
	v_max3_f32 v3, v3, v99, v107
	v_max3_f32 v3, v3, v108, v112
	v_max3_f32 v3, v3, v109, v113
	v_max3_f32 v3, v3, v110, v114
	v_max3_f32 v3, v3, v111, v115
	v_max3_f32 v3, v3, v116, v120
	v_max3_f32 v3, v3, v117, v121
	v_max3_f32 v3, v3, v118, v122
	v_max3_f32 v3, v3, v119, v123
	v_and_b32_e32 v125, 64, v198
	v_mov_b32_e32 v124, v3
	v_mov_b32_e32 v255, v3
	s_nop 1
	v_permlane16_swap_b32_e32 v124, v255
	s_waitcnt lgkmcnt(0)
	v_max_f32_e32 v3, v124, v255
	v_mov_b32_e32 v124, v3
	v_mov_b32_e32 v255, v3
	s_nop 1
	v_permlane32_swap_b32_e32 v124, v255
	s_waitcnt lgkmcnt(0)
; #define LAS __attribute__((address_space(3)))
; DI float fast_exp2(float x) { return __builtin_amdgcn_exp2f(x); }
; #define MFMA16(a, b, c) __builtin_amdgcn_mfma_f32_16x16x32_bf16((a), (b), (c), 0, 0, 0)
; DI u32x2 tr4(const LAS unsigned char* p) { return __builtin_bit_cast(u32x2, __builtin_amdgcn_ds_read_tr16_b64_v4i16((LAS v4i16_t*)p)); }
; DI bf16x8 packp(f32x4 a, f32x4 b) { return __builtin_bit_cast(bf16x8, pack8(a, b)); }
; DI void at_pv(AtState& S, const f32x4 (&s1)[4], const f32x4 (&s2)[4], float alpha, float ps1, float ps2, const LAS unsigned char* buf, int hh, int fq, int tq, int tp) {
;     S.l1 = S.l1 * alpha + ps1; S.l2 = S.l2 * alpha + ps2;
; #pragma unroll
;     for (int dt = 0; dt < 4; ++dt) { S.O1[dt] = S.O1[dt] * alpha; S.O2[dt] = S.O2[dt] * alpha; }
;     bf16x8 p1[2], p2[2];
; #pragma unroll
;     for (int s = 0; s < 2; ++s) { p1[s] = packp(s1[2 * s], s1[2 * s + 1]); p2[s] = packp(s2[2 * s], s2[2 * s + 1]); }
; #pragma unroll
;     for (int dh = 0; dh < 2; ++dh) {
;         bf16x8 vt[2][2];
; #pragma unroll
;         for (int d2 = 0; d2 < 2; ++d2)
; #pragma unroll
;             for (int s = 0; s < 2; ++s) { const int dt = 2 * dh + d2; const LAS unsigned char* vr = buf + AT_V + (32 * s + 4 * fq + tq) * 288 + (hh * 64 + 16 * dt + 4 * tp) * 2; vt[d2][s] = cat44(tr4(vr), tr4(vr + 16 * 288)); }
;         __builtin_amdgcn_s_setprio(1);
; #pragma unroll
;         for (int s = 0; s < 2; ++s)
; #pragma unroll
;             for (int d2 = 0; d2 < 2; ++d2) { const int dt = 2 * dh + d2; S.O1[dt] = MFMA16(vt[d2][s], p1[s], S.O1[dt]); S.O2[dt] = MFMA16(vt[d2][s], p2[s], S.O2[dt]); }
; template <int VAR>
; DI void attn_tile(AtState& S, const LAS unsigned char* buf, const bf16x8 q1, const bf16x8 q2, int kt, bool diag, int qpos0, int qpos_l, float slope2, float adv, float decay, int hh, int fr, int fq) {
;     ...
;             lm = fmaxf(lm, __shfl_xor(lm, 16)); lm = fmaxf(lm, __shfl_xor(lm, 32));
;             const float bump = fmaxf(lm, 0.f);
;             const float alpha = decay * fast_exp2(-bump); S.ref += bump;
; #pragma unroll
;             for (int k4 = 0; k4 < 4; ++k4) { s1[k4] = s1[k4] - bump; s2[k4] = s2[k4] - bump; S.cinit[k4] = S.cinit[k4] - bump; }
;             at_exp(s1, s2, ps1, ps2);
;             at_pv(S, s1, s2, alpha, ps1, ps2, buf, hh, fq, tq, tp);
	v_max3_f32 v124, v255, v124, 0
	v_sub_f32_e32 v126, v79, v124
	v_sub_f32_e32 v127, v78, v124
	v_sub_f32_e32 v128, v77, v124
	v_sub_f32_e32 v129, v76, v124
	v_sub_f32_e32 v130, v83, v124
	v_sub_f32_e32 v131, v82, v124
	v_sub_f32_e32 v132, v81, v124
	v_sub_f32_e32 v133, v80, v124
	v_sub_f32_e32 v134, v99, v124
	v_sub_f32_e32 v135, v98, v124
	v_sub_f32_e32 v137, v97, v124
	v_sub_f32_e32 v138, v96, v124
	v_sub_f32_e32 v139, v107, v124
	v_sub_f32_e32 v151, v106, v124
	v_sub_f32_e32 v158, v105, v124
	v_sub_f32_e32 v159, v104, v124
	v_exp_f32_e32 v216, v129
	v_exp_f32_e32 v220, v133
	v_exp_f32_e32 v217, v128
	v_exp_f32_e32 v221, v132
	v_exp_f32_e32 v218, v127
	v_exp_f32_e32 v222, v131
	v_exp_f32_e32 v219, v126
	v_exp_f32_e32 v223, v130
	v_sub_f32_e32 v237, v111, v124
	v_sub_f32_e32 v236, v110, v124
	v_sub_f32_e32 v233, v109, v124
	v_sub_f32_e32 v232, v108, v124
	v_sub_f32_e32 v239, v115, v124
	v_sub_f32_e32 v238, v114, v124
	v_sub_f32_e32 v235, v113, v124
	v_sub_f32_e32 v234, v112, v124
	v_exp_f32_e32 v224, v138
	v_exp_f32_e32 v226, v159
	v_exp_f32_e32 v225, v137
	v_exp_f32_e32 v227, v158
	v_exp_f32_e32 v228, v135
	v_exp_f32_e32 v230, v151
	v_exp_f32_e32 v229, v134
	v_exp_f32_e32 v231, v139
	v_sub_f32_e32 v119, v119, v124
	v_sub_f32_e32 v118, v118, v124
	v_sub_f32_e32 v117, v117, v124
	v_sub_f32_e32 v116, v116, v124
	v_sub_f32_e32 v123, v123, v124
	v_sub_f32_e32 v122, v122, v124
	v_sub_f32_e32 v121, v121, v124
	v_sub_f32_e32 v120, v120, v124
	v_exp_f32_e32 v232, v232
	v_exp_f32_e32 v234, v234
	v_exp_f32_e32 v233, v233
	v_exp_f32_e32 v235, v235
	v_exp_f32_e32 v236, v236
	v_exp_f32_e32 v238, v238
	v_exp_f32_e32 v237, v237
	v_exp_f32_e32 v239, v239
	v_exp_f32_e32 v240, v116
	v_exp_f32_e32 v242, v120
	v_exp_f32_e32 v241, v117
	v_exp_f32_e32 v243, v121
	v_exp_f32_e32 v244, v118
	v_exp_f32_e32 v246, v122
	v_exp_f32_e32 v245, v119
	v_exp_f32_e32 v247, v123
	v_pk_add_f32 v[110:111], v[228:229], v[218:219]
	v_pk_add_f32 v[108:109], v[224:225], v[216:217]
	v_pk_add_f32 v[114:115], v[230:231], v[222:223]
	v_pk_add_f32 v[112:113], v[226:227], v[220:221]
	v_pk_add_f32 v[108:109], v[232:233], v[108:109]
	v_pk_add_f32 v[110:111], v[236:237], v[110:111]
	v_pk_add_f32 v[112:113], v[234:235], v[112:113]
	v_pk_add_f32 v[114:115], v[238:239], v[114:115]
	v_pk_add_f32 v[110:111], v[244:245], v[110:111]
	v_pk_add_f32 v[108:109], v[240:241], v[108:109]
	v_pk_add_f32 v[114:115], v[246:247], v[114:115]
	v_pk_add_f32 v[112:113], v[242:243], v[112:113]
	v_cvt_pk_bf16_f32 v216, v216, v217
	v_cvt_pk_bf16_f32 v217, v218, v219
	v_cvt_pk_bf16_f32 v218, v224, v225
	v_cvt_pk_bf16_f32 v219, v228, v229
	v_cvt_pk_bf16_f32 v220, v220, v221
	v_cvt_pk_bf16_f32 v221, v222, v223
	v_cvt_pk_bf16_f32 v222, v226, v227
	v_cvt_pk_bf16_f32 v223, v230, v231
	v_cvt_pk_bf16_f32 v224, v232, v233
	v_cvt_pk_bf16_f32 v225, v236, v237
	v_cvt_pk_bf16_f32 v226, v240, v241
	v_cvt_pk_bf16_f32 v227, v244, v245
	v_cvt_pk_bf16_f32 v228, v234, v235
	v_cvt_pk_bf16_f32 v229, v238, v239
	v_cvt_pk_bf16_f32 v230, v242, v243
	v_cvt_pk_bf16_f32 v231, v246, v247
	ds_read_b64_tr_b16 v[232:233], v208 offset:17408
	ds_read_b64_tr_b16 v[236:237], v208 offset:17440
	ds_read_b64_tr_b16 v[234:235], v208 offset:22016
	ds_read_b64_tr_b16 v[240:241], v208 offset:26624
	ds_read_b64_tr_b16 v[242:243], v208 offset:31232
	ds_read_b64_tr_b16 v[238:239], v208 offset:22048
	ds_read_b64_tr_b16 v[244:245], v208 offset:26656
	ds_read_b64_tr_b16 v[246:247], v208 offset:31264
	v_exp_f32_e64 v125, -v124
	v_mov_b32_e32 v116, v112
	v_mov_b32_e32 v117, v108
	v_mov_b32_e32 v108, v113
	v_mov_b32_e32 v112, v114
	v_mov_b32_e32 v113, v110
	v_mov_b32_e32 v110, v115
	v_pk_add_f32 v[108:109], v[116:117], v[108:109]
	v_pk_add_f32 v[110:111], v[112:113], v[110:111]
	v_mul_f32_e32 v136, v150, v125
	v_pk_add_f32 v[108:109], v[108:109], v[110:111]
	v_add_f32_e32 v3, v215, v124
	v_sub_f32_e32 v79, v47, v124
	v_sub_f32_e32 v78, v46, v124
	v_sub_f32_e32 v77, v45, v124
	v_sub_f32_e32 v76, v44, v124
	v_sub_f32_e32 v99, v51, v124
	v_sub_f32_e32 v98, v50, v124
	v_sub_f32_e32 v97, v49, v124
	v_sub_f32_e32 v96, v48, v124
	v_sub_f32_e32 v107, v55, v124
	v_sub_f32_e32 v106, v54, v124
	v_sub_f32_e32 v105, v53, v124
	v_sub_f32_e32 v104, v52, v124
	v_sub_f32_e32 v83, v59, v124
	v_sub_f32_e32 v82, v58, v124
	v_sub_f32_e32 v81, v57, v124
	v_sub_f32_e32 v80, v56, v124
	v_pk_fma_f32 v[158:159], v[156:157], v[136:137], v[108:109] op_sel_hi:[1,0,1]
	v_pk_mul_f32 v[110:111], v[66:67], v[136:137] op_sel_hi:[1,0]
	v_pk_mul_f32 v[108:109], v[64:65], v[136:137] op_sel_hi:[1,0]
	v_pk_mul_f32 v[114:115], v[74:75], v[136:137] op_sel_hi:[1,0]
	v_pk_mul_f32 v[112:113], v[72:73], v[136:137] op_sel_hi:[1,0]
	v_pk_mul_f32 v[118:119], v[62:63], v[136:137] op_sel_hi:[1,0]
	v_pk_mul_f32 v[116:117], v[60:61], v[136:137] op_sel_hi:[1,0]
	v_pk_mul_f32 v[122:123], v[70:71], v[136:137] op_sel_hi:[1,0]
	v_pk_mul_f32 v[120:121], v[68:69], v[136:137] op_sel_hi:[1,0]
	v_pk_mul_f32 v[126:127], v[90:91], v[136:137] op_sel_hi:[1,0]
	v_pk_mul_f32 v[124:125], v[88:89], v[136:137] op_sel_hi:[1,0]
	v_pk_mul_f32 v[130:131], v[102:103], v[136:137] op_sel_hi:[1,0]
	v_pk_mul_f32 v[128:129], v[100:101], v[136:137] op_sel_hi:[1,0]
	v_pk_mul_f32 v[134:135], v[86:87], v[136:137] op_sel_hi:[1,0]
	v_pk_mul_f32 v[132:133], v[84:85], v[136:137] op_sel_hi:[1,0]
	v_pk_mul_f32 v[138:139], v[94:95], v[136:137] op_sel_hi:[1,0]
	v_pk_mul_f32 v[136:137], v[92:93], v[136:137] op_sel_hi:[1,0]
	s_setprio 1
	s_waitcnt lgkmcnt(5)
; #define LAS __attribute__((address_space(3)))
; #define MFMA16(a, b, c) __builtin_amdgcn_mfma_f32_16x16x32_bf16((a), (b), (c), 0, 0, 0)
; DI u32x2 tr4(const LAS unsigned char* p) { return __builtin_bit_cast(u32x2, __builtin_amdgcn_ds_read_tr16_b64_v4i16((LAS v4i16_t*)p)); }
; DI void at_pv(AtState& S, const f32x4 (&s1)[4], const f32x4 (&s2)[4], float alpha, float ps1, float ps2, const LAS unsigned char* buf, int hh, int fq, int tq, int tp) {
;     ...
;     for (int dh = 0; dh < 2; ++dh) {
;         bf16x8 vt[2][2];
; #pragma unroll
;         for (int d2 = 0; d2 < 2; ++d2)
; #pragma unroll
;             for (int s = 0; s < 2; ++s) { const int dt = 2 * dh + d2; const LAS unsigned char* vr = buf + AT_V + (32 * s + 4 * fq + tq) * 288 + (hh * 64 + 16 * dt + 4 * tp) * 2; vt[d2][s] = cat44(tr4(vr), tr4(vr + 16 * 288)); }
;         __builtin_amdgcn_s_setprio(1);
; #pragma unroll
;         for (int s = 0; s < 2; ++s)
; #pragma unroll
;             for (int d2 = 0; d2 < 2; ++d2) { const int dt = 2 * dh + d2; S.O1[dt] = MFMA16(vt[d2][s], p1[s], S.O1[dt]); S.O2[dt] = MFMA16(vt[d2][s], p2[s], S.O2[dt]); }
;         __builtin_amdgcn_s_setprio(0);
;         __builtin_amdgcn_sched_barrier(0);
;     }
	v_mfma_f32_16x16x32_bf16 v[108:111], v[232:235], v[216:219], v[108:111]
	v_mfma_f32_16x16x32_bf16 v[112:115], v[232:235], v[220:223], v[112:115]
	s_waitcnt lgkmcnt(2)
	v_mfma_f32_16x16x32_bf16 v[232:235], v[236:239], v[216:219], v[116:119]
	v_mfma_f32_16x16x32_bf16 v[236:239], v[236:239], v[220:223], v[120:123]
	v_mfma_f32_16x16x32_bf16 v[120:123], v[240:243], v[224:227], v[108:111]
	v_mfma_f32_16x16x32_bf16 v[116:119], v[240:243], v[228:231], v[112:115]
	s_waitcnt lgkmcnt(0)
	v_mfma_f32_16x16x32_bf16 v[112:115], v[244:247], v[224:227], v[232:235]
	v_mfma_f32_16x16x32_bf16 v[108:111], v[244:247], v[228:231], v[236:239]
	s_setprio 0
	s_nop 0
	ds_read_b64_tr_b16 v[232:233], v208 offset:17472
	ds_read_b64_tr_b16 v[236:237], v208 offset:17504
	ds_read_b64_tr_b16 v[234:235], v208 offset:22080
	ds_read_b64_tr_b16 v[238:239], v208 offset:22112
	ds_read_b64_tr_b16 v[240:241], v208 offset:26688
	ds_read_b64_tr_b16 v[242:243], v208 offset:31296
	ds_read_b64_tr_b16 v[246:247], v208 offset:31328
	ds_read_b64_tr_b16 v[244:245], v208 offset:26720
	s_setprio 1
	s_waitcnt lgkmcnt(5)
	v_mfma_f32_16x16x32_bf16 v[124:127], v[232:235], v[216:219], v[124:127]
	v_mfma_f32_16x16x32_bf16 v[128:131], v[232:235], v[220:223], v[128:131]
	s_waitcnt lgkmcnt(4)
	v_mfma_f32_16x16x32_bf16 v[216:219], v[236:239], v[216:219], v[132:135]
	v_mfma_f32_16x16x32_bf16 v[220:223], v[236:239], v[220:223], v[136:139]
	s_waitcnt lgkmcnt(2)
	v_mfma_f32_16x16x32_bf16 v[136:139], v[240:243], v[224:227], v[124:127]
	v_mfma_f32_16x16x32_bf16 v[132:135], v[240:243], v[228:231], v[128:131]
	s_waitcnt lgkmcnt(0)
	v_mfma_f32_16x16x32_bf16 v[128:131], v[244:247], v[224:227], v[216:219]
	v_mfma_f32_16x16x32_bf16 v[124:127], v[244:247], v[228:231], v[220:223]
	s_setprio 0
	s_cbranch_execnz .LBB0_1380

; #define LAS __attribute__((address_space(3)))
; DI float fast_exp2(float x) { return __builtin_amdgcn_exp2f(x); }
; #define MFMA16(a, b, c) __builtin_amdgcn_mfma_f32_16x16x32_bf16((a), (b), (c), 0, 0, 0)
; DI void lds_barrier() { asm volatile("s_waitcnt lgkmcnt(0)" ::: "memory"); __builtin_amdgcn_s_barrier(); asm volatile("" ::: "memory"); }
; DI void at_qk(f32x4 (&s1)[4], f32x4 (&s2)[4], const LAS unsigned char* buf, const bf16x8 q1, const bf16x8 q2, const f32x4 (&ci)[4], int hh, int fr, int fq) {
; #pragma unroll
;     for (int k4 = 0; k4 < 4; ++k4) { const LAS unsigned char* kr = buf + AT_K + (16 * k4 + fr) * 272 + hh * 128 + fq * 16;
;         s1[k4] = MFMA16(ld8l(kr), q1, ci[k4]); s2[k4] = MFMA16(ld8l(kr + 64), q2, ci[k4]); }
; }
; DI void at_exp(f32x4 (&s1)[4], f32x4 (&s2)[4], float& ps1, float& ps2) {
;     f32x4 a1 = (f32x4){0.f, 0.f, 0.f, 0.f}, a2 = a1;
; #pragma unroll
;     for (int k4 = 0; k4 < 4; ++k4) {
; #pragma unroll
;         for (int j = 0; j < 4; ++j) { s1[k4][j] = fast_exp2(s1[k4][j]); s2[k4][j] = fast_exp2(s2[k4][j]); }
;         a1 = a1 + s1[k4]; a2 = a2 + s2[k4]; }
;     ps1 = (a1[0] + a1[1]) + (a1[2] + a1[3]); ps2 = (a2[0] + a2[1]) + (a2[2] + a2[3]);
; }
; template <int VAR>
; DI void attn_segment(const Args& a, const Frame& F, int l, int qrow0, int qpos0, int hp, int ntile, int nf32, const float* ck, const float* cv, int prow0) {
;     ...
;             lds_barrier();
;             if (kt + 1 >= ntile) break;
;             atb_issue(ra, pb + (size_t)(kt + 3 < nl ? kt + 3 : nl) * TSTR, voff);
;             attn_tile<VAR>(S, F.lds + ((kt + 1) & 1) * AT_BUF, q1, q2, kt + 1, kt + 2 == ntile, qpos0, qpos_l, slope2, adv, decay, hh, fr, fq);
.Lcommit_done_A:
	s_waitcnt lgkmcnt(0)
	s_barrier
	s_add_i32 s14, s26, -2
	s_cmp_ge_i32 s14, s24
	s_mov_b64 s[14:15], -1
	s_cbranch_scc1 .LBB0_1375
	s_min_i32 s14, s26, s25
	s_ashr_i32 s15, s14, 31
	s_lshl_b64 s[14:15], s[14:15], 18
	s_add_u32 s14, s0, s14
	s_addc_u32 s15, s1, s15
	v_lshl_add_u64 v[16:17], s[14:15], 0, v[144:145]
	v_lshl_add_u64 v[24:25], s[14:15], 0, v[146:147]
	global_load_dwordx4 v[12:15], v[16:17], off offset:1024
	s_nop 0
	global_load_dwordx4 v[16:19], v[16:17], off offset:1536
	s_nop 0
	global_load_dwordx4 v[20:23], v[24:25], off offset:1024
	s_nop 0
	global_load_dwordx4 v[24:27], v[24:25], off offset:1536
	s_cmpk_lg_i32 s28, 0x41
	s_mov_b64 s[14:15], -1
	s_cbranch_scc0 .LBB0_1391
	ds_read_b128 v[44:47], v213 offset:35840
	ds_read_b128 v[48:51], v213 offset:35904
	ds_read_b128 v[52:55], v213 offset:40192
	ds_read_b128 v[56:59], v213 offset:40256
	ds_read_b128 v[60:63], v213 offset:44544
	ds_read_b128 v[64:67], v213 offset:44608
	ds_read_b128 v[68:71], v213 offset:48896
	ds_read_b128 v[72:75], v213 offset:48960
	s_waitcnt lgkmcnt(7)
	v_mfma_f32_16x16x32_bf16 v[44:47], v[44:47], v[4:7], v[76:79]
	v_add_f32_e32 v215, v205, v3
	s_waitcnt lgkmcnt(6)
	v_mfma_f32_16x16x32_bf16 v[48:51], v[48:51], v[8:11], v[76:79]
	s_waitcnt lgkmcnt(5)
	v_mfma_f32_16x16x32_bf16 v[52:55], v[52:55], v[4:7], v[96:99]
	s_nop 2
	v_exp_f32_e32 v164, v44
	v_exp_f32_e32 v165, v45
	v_exp_f32_e32 v168, v46
	s_waitcnt lgkmcnt(4)
	v_mfma_f32_16x16x32_bf16 v[56:59], v[56:59], v[8:11], v[96:99]
	v_exp_f32_e32 v169, v47
	v_exp_f32_e32 v162, v48
	v_exp_f32_e32 v163, v49
	s_waitcnt lgkmcnt(3)
	v_mfma_f32_16x16x32_bf16 v[60:63], v[60:63], v[4:7], v[104:107]
	v_exp_f32_e32 v166, v50
	v_exp_f32_e32 v167, v51
	v_exp_f32_e32 v172, v52
	s_waitcnt lgkmcnt(2)
	v_mfma_f32_16x16x32_bf16 v[44:47], v[64:67], v[8:11], v[104:107]
	v_exp_f32_e32 v170, v56
	v_exp_f32_e32 v173, v53
	v_exp_f32_e32 v176, v54
	s_waitcnt lgkmcnt(1)
	v_mfma_f32_16x16x32_bf16 v[48:51], v[68:71], v[4:7], v[80:83]
	v_exp_f32_e32 v177, v55
	v_exp_f32_e32 v174, v58
	v_exp_f32_e32 v175, v59
	s_waitcnt lgkmcnt(0)
	v_mfma_f32_16x16x32_bf16 v[64:67], v[72:75], v[8:11], v[80:83]
	v_exp_f32_e32 v171, v57
	v_exp_f32_e32 v180, v60
	v_exp_f32_e32 v178, v44
	v_exp_f32_e32 v181, v61
	v_exp_f32_e32 v179, v45
	v_exp_f32_e32 v184, v62
	v_exp_f32_e32 v185, v63
	v_exp_f32_e32 v182, v46
	v_exp_f32_e32 v183, v47
	v_exp_f32_e32 v188, v48
	v_exp_f32_e32 v186, v64
	v_exp_f32_e32 v189, v49
	v_exp_f32_e32 v192, v50
	v_exp_f32_e32 v193, v51
	v_exp_f32_e32 v190, v66
	v_exp_f32_e32 v191, v67
	v_exp_f32_e32 v187, v65
	v_pk_add_f32 v[52:53], v[168:169], v[176:177]
	v_pk_add_f32 v[54:55], v[164:165], v[172:173]
	v_pk_add_f32 v[56:57], v[166:167], v[174:175]
	v_pk_add_f32 v[58:59], v[162:163], v[170:171]
	v_pk_add_f32 v[44:45], v[54:55], v[180:181]
	v_pk_add_f32 v[46:47], v[52:53], v[184:185]
	v_pk_add_f32 v[52:53], v[58:59], v[178:179]
	v_pk_add_f32 v[54:55], v[56:57], v[182:183]
	v_pk_add_f32 v[46:47], v[46:47], v[192:193]
	v_pk_add_f32 v[44:45], v[44:45], v[188:189]
	v_pk_add_f32 v[48:49], v[54:55], v[190:191]
	v_pk_add_f32 v[50:51], v[52:53], v[186:187]
	v_add_f32_e32 v52, v50, v51
	v_add_f32_e32 v53, v44, v45
	v_add_f32_e32 v50, v48, v49
	v_add_f32_e32 v51, v46, v47
	v_pk_add_f32 v[194:195], v[52:53], v[50:51]
	v_add_f32_e32 v44, v195, v194
	v_cmp_ngt_f32_e32 vcc, s65, v44
	s_cbranch_vccz .LBB0_1395
	ds_read_b128 v[44:47], v213 offset:35840
	ds_read_b128 v[48:51], v213 offset:35904
	ds_read_b128 v[52:55], v213 offset:40192
	ds_read_b128 v[56:59], v213 offset:40256
	ds_read_b128 v[60:63], v213 offset:44544
	ds_read_b128 v[64:67], v213 offset:44608
	ds_read_b128 v[68:71], v213 offset:48896
	ds_read_b128 v[72:75], v213 offset:48960
	s_waitcnt lgkmcnt(7)
	v_mfma_f32_16x16x32_bf16 v[44:47], v[44:47], v[4:7], v[76:79]
	s_waitcnt lgkmcnt(6)
	v_mfma_f32_16x16x32_bf16 v[48:51], v[48:51], v[8:11], v[76:79]
	s_waitcnt lgkmcnt(5)
	v_mfma_f32_16x16x32_bf16 v[52:55], v[52:55], v[4:7], v[96:99]
	s_waitcnt lgkmcnt(4)
	v_mfma_f32_16x16x32_bf16 v[56:59], v[56:59], v[8:11], v[96:99]
	s_waitcnt lgkmcnt(3)
	v_mfma_f32_16x16x32_bf16 v[60:63], v[60:63], v[4:7], v[104:107]
	s_waitcnt lgkmcnt(2)
	v_mfma_f32_16x16x32_bf16 v[64:67], v[64:67], v[8:11], v[104:107]
	s_waitcnt lgkmcnt(1)
	v_mfma_f32_16x16x32_bf16 v[68:71], v[68:71], v[4:7], v[80:83]
	s_waitcnt lgkmcnt(0)
	v_mfma_f32_16x16x32_bf16 v[72:75], v[72:75], v[8:11], v[80:83]
	v_max3_f32 v84, v44, v48, s60
	v_max3_f32 v84, v84, v45, v49
	v_max3_f32 v84, v84, v46, v50
	v_max3_f32 v84, v84, v47, v51
	v_max3_f32 v84, v84, v52, v56
	v_max3_f32 v84, v84, v53, v57
	v_max3_f32 v84, v84, v54, v58
	v_max3_f32 v84, v84, v55, v59
	v_max3_f32 v84, v84, v60, v64
	v_max3_f32 v84, v84, v61, v65
	v_max3_f32 v84, v84, v62, v66
	v_max3_f32 v84, v84, v63, v67
	v_max3_f32 v84, v84, v68, v72
	v_max3_f32 v84, v84, v69, v73
	v_max3_f32 v84, v84, v70, v74
	v_max3_f32 v84, v84, v71, v75
	v_and_b32_e32 v86, 64, v198
	v_mov_b32_e32 v85, v84
	v_mov_b32_e32 v255, v84
	s_nop 1
	v_permlane16_swap_b32_e32 v85, v255
	s_waitcnt lgkmcnt(0)
	v_max_f32_e32 v84, v85, v255
	v_mov_b32_e32 v85, v84
	v_mov_b32_e32 v255, v84
	s_nop 1
	v_permlane32_swap_b32_e32 v85, v255
	s_waitcnt lgkmcnt(0)
; #define LAS __attribute__((address_space(3)))
; DI float fast_exp2(float x) { return __builtin_amdgcn_exp2f(x); }
; #define MFMA16(a, b, c) __builtin_amdgcn_mfma_f32_16x16x32_bf16((a), (b), (c), 0, 0, 0)
; DI u32x2 tr4(const LAS unsigned char* p) { return __builtin_bit_cast(u32x2, __builtin_amdgcn_ds_read_tr16_b64_v4i16((LAS v4i16_t*)p)); }
; DI void at_pv(AtState& S, const f32x4 (&s1)[4], const f32x4 (&s2)[4], float alpha, float ps1, float ps2, const LAS unsigned char* buf, int hh, int fq, int tq, int tp) {
;     S.l1 = S.l1 * alpha + ps1; S.l2 = S.l2 * alpha + ps2;
; #pragma unroll
;     for (int dt = 0; dt < 4; ++dt) { S.O1[dt] = S.O1[dt] * alpha; S.O2[dt] = S.O2[dt] * alpha; }
;     bf16x8 p1[2], p2[2];
; #pragma unroll
;     for (int s = 0; s < 2; ++s) { p1[s] = packp(s1[2 * s], s1[2 * s + 1]); p2[s] = packp(s2[2 * s], s2[2 * s + 1]); }
; #pragma unroll
;     for (int dh = 0; dh < 2; ++dh) {
;         bf16x8 vt[2][2];
; #pragma unroll
;         for (int d2 = 0; d2 < 2; ++d2)
; #pragma unroll
;             for (int s = 0; s < 2; ++s) { const int dt = 2 * dh + d2; const LAS unsigned char* vr = buf + AT_V + (32 * s + 4 * fq + tq) * 288 + (hh * 64 + 16 * dt + 4 * tp) * 2; vt[d2][s] = cat44(tr4(vr), tr4(vr + 16 * 288)); }
;         __builtin_amdgcn_s_setprio(1);
; #pragma unroll
;         for (int s = 0; s < 2; ++s)
; #pragma unroll
;             for (int d2 = 0; d2 < 2; ++d2) { const int dt = 2 * dh + d2; S.O1[dt] = MFMA16(vt[d2][s], p1[s], S.O1[dt]); S.O2[dt] = MFMA16(vt[d2][s], p2[s], S.O2[dt]); }
;         __builtin_amdgcn_s_setprio(0);
;         __builtin_amdgcn_sched_barrier(0);
;     }
; }
; template <int VAR>
; DI void attn_tile(AtState& S, const LAS unsigned char* buf, const bf16x8 q1, const bf16x8 q2, int kt, bool diag, int qpos0, int qpos_l, float slope2, float adv, float decay, int hh, int fr, int fq) {
;     ...
;             lm = fmaxf(lm, __shfl_xor(lm, 16)); lm = fmaxf(lm, __shfl_xor(lm, 32));
;             const float bump = fmaxf(lm, 0.f);
;             const float alpha = decay * fast_exp2(-bump); S.ref += bump;
; #pragma unroll
;             for (int k4 = 0; k4 < 4; ++k4) { s1[k4] = s1[k4] - bump; s2[k4] = s2[k4] - bump; S.cinit[k4] = S.cinit[k4] - bump; }
;             at_exp(s1, s2, ps1, ps2);
;             at_pv(S, s1, s2, alpha, ps1, ps2, buf, hh, fq, tq, tp);
	v_max3_f32 v84, v255, v85, 0
	v_sub_f32_e32 v86, v47, v84
	v_sub_f32_e32 v87, v46, v84
	v_sub_f32_e32 v88, v45, v84
	v_sub_f32_e32 v89, v44, v84
	v_sub_f32_e32 v90, v51, v84
	v_sub_f32_e32 v91, v50, v84
	v_sub_f32_e32 v92, v49, v84
	v_sub_f32_e32 v93, v48, v84
	v_sub_f32_e32 v94, v55, v84
	v_sub_f32_e32 v95, v54, v84
	v_sub_f32_e32 v101, v53, v84
	v_sub_f32_e32 v102, v52, v84
	v_sub_f32_e32 v103, v59, v84
	v_sub_f32_e32 v151, v58, v84
	v_sub_f32_e32 v156, v57, v84
	v_sub_f32_e32 v157, v56, v84
	v_exp_f32_e32 v216, v89
	v_exp_f32_e32 v220, v93
	v_exp_f32_e32 v217, v88
	v_exp_f32_e32 v221, v92
	v_exp_f32_e32 v218, v87
	v_exp_f32_e32 v222, v91
	v_exp_f32_e32 v219, v86
	v_exp_f32_e32 v223, v90
	v_sub_f32_e32 v237, v63, v84
	v_sub_f32_e32 v236, v62, v84
	v_sub_f32_e32 v233, v61, v84
	v_sub_f32_e32 v232, v60, v84
	v_sub_f32_e32 v239, v67, v84
	v_sub_f32_e32 v238, v66, v84
	v_sub_f32_e32 v235, v65, v84
	v_sub_f32_e32 v234, v64, v84
	v_exp_f32_e32 v224, v102
	v_exp_f32_e32 v226, v157
	v_exp_f32_e32 v225, v101
	v_exp_f32_e32 v227, v156
	v_exp_f32_e32 v228, v95
	v_exp_f32_e32 v230, v151
	v_exp_f32_e32 v229, v94
	v_exp_f32_e32 v231, v103
	v_sub_f32_e32 v71, v71, v84
	v_sub_f32_e32 v70, v70, v84
	v_sub_f32_e32 v69, v69, v84
	v_sub_f32_e32 v68, v68, v84
	v_sub_f32_e32 v75, v75, v84
	v_sub_f32_e32 v74, v74, v84
	v_sub_f32_e32 v73, v73, v84
	v_sub_f32_e32 v72, v72, v84
	v_exp_f32_e32 v232, v232
	v_exp_f32_e32 v234, v234
	v_exp_f32_e32 v233, v233
	v_exp_f32_e32 v235, v235
	v_exp_f32_e32 v236, v236
	v_exp_f32_e32 v238, v238
	v_exp_f32_e32 v237, v237
	v_exp_f32_e32 v239, v239
	v_exp_f32_e32 v240, v68
	v_exp_f32_e32 v242, v72
	v_exp_f32_e32 v241, v69
	v_exp_f32_e32 v243, v73
	v_exp_f32_e32 v244, v70
	v_exp_f32_e32 v246, v74
	v_exp_f32_e32 v245, v71
	v_exp_f32_e32 v247, v75
	v_pk_add_f32 v[62:63], v[228:229], v[218:219]
	v_pk_add_f32 v[60:61], v[224:225], v[216:217]
	v_pk_add_f32 v[66:67], v[230:231], v[222:223]
	v_pk_add_f32 v[64:65], v[226:227], v[220:221]
	v_pk_add_f32 v[60:61], v[232:233], v[60:61]
	v_pk_add_f32 v[62:63], v[236:237], v[62:63]
	v_pk_add_f32 v[64:65], v[234:235], v[64:65]
	v_pk_add_f32 v[66:67], v[238:239], v[66:67]
	v_pk_add_f32 v[62:63], v[244:245], v[62:63]
	v_pk_add_f32 v[60:61], v[240:241], v[60:61]
	v_pk_add_f32 v[66:67], v[246:247], v[66:67]
	v_pk_add_f32 v[64:65], v[242:243], v[64:65]
	v_cvt_pk_bf16_f32 v216, v216, v217
	v_cvt_pk_bf16_f32 v217, v218, v219
	v_cvt_pk_bf16_f32 v218, v224, v225
	v_cvt_pk_bf16_f32 v219, v228, v229
	v_cvt_pk_bf16_f32 v220, v220, v221
	v_cvt_pk_bf16_f32 v221, v222, v223
	v_cvt_pk_bf16_f32 v222, v226, v227
	v_cvt_pk_bf16_f32 v223, v230, v231
	v_cvt_pk_bf16_f32 v224, v232, v233
	v_cvt_pk_bf16_f32 v225, v236, v237
	v_cvt_pk_bf16_f32 v226, v240, v241
	v_cvt_pk_bf16_f32 v227, v244, v245
	v_cvt_pk_bf16_f32 v228, v234, v235
	v_cvt_pk_bf16_f32 v229, v238, v239
	v_cvt_pk_bf16_f32 v230, v242, v243
	v_cvt_pk_bf16_f32 v231, v246, v247
	ds_read_b64_tr_b16 v[232:233], v208 offset:53248
	ds_read_b64_tr_b16 v[236:237], v208 offset:53280
	ds_read_b64_tr_b16 v[234:235], v208 offset:57856
	ds_read_b64_tr_b16 v[240:241], v208 offset:62464
	ds_read_b64_tr_b16 v[242:243], v209 offset:4608
	ds_read_b64_tr_b16 v[238:239], v208 offset:57888
	ds_read_b64_tr_b16 v[244:245], v208 offset:62496
	ds_read_b64_tr_b16 v[246:247], v210 offset:4608
	v_exp_f32_e64 v85, -v84
	v_mov_b32_e32 v68, v64
	v_mov_b32_e32 v69, v60
	v_mov_b32_e32 v60, v65
	v_mov_b32_e32 v64, v66
	v_mov_b32_e32 v65, v62
	v_mov_b32_e32 v62, v67
	v_pk_add_f32 v[60:61], v[68:69], v[60:61]
	v_pk_add_f32 v[62:63], v[64:65], v[62:63]
	v_mul_f32_e32 v100, v150, v85
	v_pk_add_f32 v[60:61], v[60:61], v[62:63]
	v_add_f32_e32 v214, v215, v84
	v_sub_f32_e32 v47, v79, v84
	v_sub_f32_e32 v46, v78, v84
	v_sub_f32_e32 v45, v77, v84
	v_sub_f32_e32 v44, v76, v84
	v_sub_f32_e32 v51, v99, v84
	v_sub_f32_e32 v50, v98, v84
	v_sub_f32_e32 v49, v97, v84
	v_sub_f32_e32 v48, v96, v84
	v_sub_f32_e32 v55, v107, v84
	v_sub_f32_e32 v54, v106, v84
	v_sub_f32_e32 v53, v105, v84
	v_sub_f32_e32 v52, v104, v84
	v_sub_f32_e32 v59, v83, v84
	v_sub_f32_e32 v58, v82, v84
	v_sub_f32_e32 v57, v81, v84
	v_sub_f32_e32 v56, v80, v84
	v_pk_fma_f32 v[156:157], v[158:159], v[100:101], v[60:61] op_sel_hi:[1,0,1]
	v_pk_mul_f32 v[62:63], v[122:123], v[100:101] op_sel_hi:[1,0]
	v_pk_mul_f32 v[60:61], v[120:121], v[100:101] op_sel_hi:[1,0]
	v_pk_mul_f32 v[66:67], v[118:119], v[100:101] op_sel_hi:[1,0]
	v_pk_mul_f32 v[64:65], v[116:117], v[100:101] op_sel_hi:[1,0]
	v_pk_mul_f32 v[70:71], v[114:115], v[100:101] op_sel_hi:[1,0]
	v_pk_mul_f32 v[68:69], v[112:113], v[100:101] op_sel_hi:[1,0]
	v_pk_mul_f32 v[74:75], v[110:111], v[100:101] op_sel_hi:[1,0]
	v_pk_mul_f32 v[72:73], v[108:109], v[100:101] op_sel_hi:[1,0]
	v_pk_mul_f32 v[86:87], v[138:139], v[100:101] op_sel_hi:[1,0]
	v_pk_mul_f32 v[84:85], v[136:137], v[100:101] op_sel_hi:[1,0]
	v_pk_mul_f32 v[90:91], v[134:135], v[100:101] op_sel_hi:[1,0]
	v_pk_mul_f32 v[88:89], v[132:133], v[100:101] op_sel_hi:[1,0]
	v_pk_mul_f32 v[94:95], v[130:131], v[100:101] op_sel_hi:[1,0]
	v_pk_mul_f32 v[92:93], v[128:129], v[100:101] op_sel_hi:[1,0]
	v_pk_mul_f32 v[102:103], v[126:127], v[100:101] op_sel_hi:[1,0]
	v_pk_mul_f32 v[100:101], v[124:125], v[100:101] op_sel_hi:[1,0]
	s_setprio 1
	s_waitcnt lgkmcnt(5)
	v_mfma_f32_16x16x32_bf16 v[60:63], v[232:235], v[216:219], v[60:63]
	v_mfma_f32_16x16x32_bf16 v[232:235], v[232:235], v[220:223], v[64:67]
	s_waitcnt lgkmcnt(2)
	v_mfma_f32_16x16x32_bf16 v[68:71], v[236:239], v[216:219], v[68:71]
	v_mfma_f32_16x16x32_bf16 v[236:239], v[236:239], v[220:223], v[72:75]
	v_mfma_f32_16x16x32_bf16 v[64:67], v[240:243], v[224:227], v[60:63]
	v_mfma_f32_16x16x32_bf16 v[72:75], v[240:243], v[228:231], v[232:235]
	s_waitcnt lgkmcnt(0)
	v_mfma_f32_16x16x32_bf16 v[60:63], v[244:247], v[224:227], v[68:71]
	v_mfma_f32_16x16x32_bf16 v[68:71], v[244:247], v[228:231], v[236:239]
	s_setprio 0
	ds_read_b64_tr_b16 v[232:233], v208 offset:53312
	s_nop 0
	ds_read_b64_tr_b16 v[236:237], v208 offset:53344
	ds_read_b64_tr_b16 v[234:235], v208 offset:57920
	ds_read_b64_tr_b16 v[238:239], v208 offset:57952
	ds_read_b64_tr_b16 v[240:241], v208 offset:62528
	ds_read_b64_tr_b16 v[242:243], v211 offset:4608
	ds_read_b64_tr_b16 v[246:247], v212 offset:4608
	ds_read_b64_tr_b16 v[244:245], v208 offset:62560
	s_setprio 1
	s_waitcnt lgkmcnt(5)
	v_mfma_f32_16x16x32_bf16 v[84:87], v[232:235], v[216:219], v[84:87]
	v_mfma_f32_16x16x32_bf16 v[232:235], v[232:235], v[220:223], v[88:91]
	s_waitcnt lgkmcnt(4)
	v_mfma_f32_16x16x32_bf16 v[92:95], v[236:239], v[216:219], v[92:95]
	v_mfma_f32_16x16x32_bf16 v[216:219], v[236:239], v[220:223], v[100:103]
	s_waitcnt lgkmcnt(2)
	v_mfma_f32_16x16x32_bf16 v[88:91], v[240:243], v[224:227], v[84:87]
	v_mfma_f32_16x16x32_bf16 v[100:103], v[240:243], v[228:231], v[232:235]
	s_waitcnt lgkmcnt(0)
	v_mfma_f32_16x16x32_bf16 v[84:87], v[244:247], v[224:227], v[92:95]
	v_mfma_f32_16x16x32_bf16 v[92:95], v[244:247], v[228:231], v[216:219]
	s_setprio 0
	s_cbranch_execnz .LBB0_1390

; #define LAS __attribute__((address_space(3)))
; DI float fast_exp2(float x) { return __builtin_amdgcn_exp2f(x); }
; #define MFMA16(a, b, c) __builtin_amdgcn_mfma_f32_16x16x32_bf16((a), (b), (c), 0, 0, 0)
; DI void at_qk(f32x4 (&s1)[4], f32x4 (&s2)[4], const LAS unsigned char* buf, const bf16x8 q1, const bf16x8 q2, const f32x4 (&ci)[4], int hh, int fr, int fq) {
; #pragma unroll
;     for (int k4 = 0; k4 < 4; ++k4) { const LAS unsigned char* kr = buf + AT_K + (16 * k4 + fr) * 272 + hh * 128 + fq * 16;
;         s1[k4] = MFMA16(ld8l(kr), q1, ci[k4]); s2[k4] = MFMA16(ld8l(kr + 64), q2, ci[k4]); }
; }
; DI void at_exp(f32x4 (&s1)[4], f32x4 (&s2)[4], float& ps1, float& ps2) {
;     f32x4 a1 = (f32x4){0.f, 0.f, 0.f, 0.f}, a2 = a1;
; #pragma unroll
;     for (int k4 = 0; k4 < 4; ++k4) {
; #pragma unroll
;         for (int j = 0; j < 4; ++j) { s1[k4][j] = fast_exp2(s1[k4][j]); s2[k4][j] = fast_exp2(s2[k4][j]); }
;         a1 = a1 + s1[k4]; a2 = a2 + s2[k4]; }
;     ps1 = (a1[0] + a1[1]) + (a1[2] + a1[3]); ps2 = (a2[0] + a2[1]) + (a2[2] + a2[3]);
; }
; template <int VAR>
; DI void attn_tile(AtState& S, const LAS unsigned char* buf, const bf16x8 q1, const bf16x8 q2, int kt, bool diag, int qpos0, int qpos_l, float slope2, float adv, float decay, int hh, int fr, int fq) {
;     ...
;         asm volatile("; attention: fast tile" ::: "memory");
;         at_qk(s1, s2, buf, q1, q2, S.cinit, hh, fr, fq);
;         S.ref += adv;
;         at_exp(s1, s2, ps1, ps2);
;         if (__any(!(ps1 + ps2 < 0x1p60f))) {
;             asm volatile("; attention: bump" ::: "memory");
;             at_qk(s1, s2, buf, q1, q2, S.cinit, hh, fr, fq);
;             float lm = -1e30f;
; #pragma unroll
;             for (int k4 = 0; k4 < 4; ++k4)
; #pragma unroll
;                 for (int j = 0; j < 4; ++j) lm = fmaxf(lm, fmaxf(s1[k4][j], s2[k4][j]));
;             lm = fmaxf(lm, __shfl_xor(lm, 16)); lm = fmaxf(lm, __shfl_xor(lm, 32));
.LBB0_1405:
	s_bitcmp1_b32 s40, 0
	s_cselect_b32 s26, 0x8c00, 0
	s_add_i32 s28, s41, s26
	s_sub_i32 s27, s40, 32
	v_add_u32_e32 v3, s28, v206
	s_cmp_gt_u32 s27, 0xffffffe0
	s_mov_b64 s[26:27], -1
	v_add_u32_e32 v3, v3, v207
	s_cbranch_scc0 .LBB0_1410
	ds_read_b128 v[62:65], v3
	ds_read_b128 v[66:69], v3 offset:64
	ds_read_b128 v[70:73], v3 offset:4352
	ds_read_b128 v[74:77], v3 offset:4416
	ds_read_b128 v[78:81], v3 offset:8704
	ds_read_b128 v[82:85], v3 offset:8768
	ds_read_b128 v[86:89], v3 offset:13056
	ds_read_b128 v[90:93], v3 offset:13120
	s_waitcnt lgkmcnt(7)
	v_mfma_f32_16x16x32_bf16 v[62:65], v[62:65], v[38:41], v[46:49]
	v_add_f32_e32 v213, v204, v212
	s_waitcnt lgkmcnt(6)
	v_mfma_f32_16x16x32_bf16 v[66:69], v[66:69], v[42:45], v[46:49]
	s_waitcnt lgkmcnt(5)
	v_mfma_f32_16x16x32_bf16 v[70:73], v[70:73], v[38:41], v[50:53]
	s_nop 2
	v_exp_f32_e32 v164, v62
	v_exp_f32_e32 v165, v63
	v_exp_f32_e32 v168, v64
	s_waitcnt lgkmcnt(4)
	v_mfma_f32_16x16x32_bf16 v[74:77], v[74:77], v[42:45], v[50:53]
	v_exp_f32_e32 v169, v65
	v_exp_f32_e32 v162, v66
	v_exp_f32_e32 v163, v67
	s_waitcnt lgkmcnt(3)
	v_mfma_f32_16x16x32_bf16 v[78:81], v[78:81], v[38:41], v[54:57]
	v_exp_f32_e32 v166, v68
	v_exp_f32_e32 v167, v69
	v_exp_f32_e32 v172, v70
	s_waitcnt lgkmcnt(2)
	v_mfma_f32_16x16x32_bf16 v[62:65], v[82:85], v[42:45], v[54:57]
	v_exp_f32_e32 v170, v74
	v_exp_f32_e32 v173, v71
	v_exp_f32_e32 v176, v72
	s_waitcnt lgkmcnt(1)
	v_mfma_f32_16x16x32_bf16 v[66:69], v[86:89], v[38:41], v[58:61]
	v_exp_f32_e32 v177, v73
	v_exp_f32_e32 v174, v76
	v_exp_f32_e32 v175, v77
	s_waitcnt lgkmcnt(0)
	v_mfma_f32_16x16x32_bf16 v[82:85], v[90:93], v[42:45], v[58:61]
	v_exp_f32_e32 v171, v75
	v_exp_f32_e32 v180, v78
	v_exp_f32_e32 v178, v62
	v_exp_f32_e32 v181, v79
	v_exp_f32_e32 v179, v63
	v_exp_f32_e32 v184, v80
	v_exp_f32_e32 v185, v81
	v_exp_f32_e32 v182, v64
	v_exp_f32_e32 v183, v65
	v_exp_f32_e32 v188, v66
	v_exp_f32_e32 v186, v82
	v_exp_f32_e32 v189, v67
	v_exp_f32_e32 v192, v68
	v_exp_f32_e32 v193, v69
	v_exp_f32_e32 v190, v84
	v_exp_f32_e32 v191, v85
	v_exp_f32_e32 v187, v83
	v_pk_add_f32 v[70:71], v[168:169], v[176:177]
	v_pk_add_f32 v[72:73], v[164:165], v[172:173]
	v_pk_add_f32 v[74:75], v[166:167], v[174:175]
	v_pk_add_f32 v[76:77], v[162:163], v[170:171]
	v_pk_add_f32 v[62:63], v[72:73], v[180:181]
	v_pk_add_f32 v[64:65], v[70:71], v[184:185]
	v_pk_add_f32 v[70:71], v[76:77], v[178:179]
	v_pk_add_f32 v[72:73], v[74:75], v[182:183]
	v_pk_add_f32 v[64:65], v[64:65], v[192:193]
	v_pk_add_f32 v[62:63], v[62:63], v[188:189]
	v_pk_add_f32 v[66:67], v[72:73], v[190:191]
	v_pk_add_f32 v[68:69], v[70:71], v[186:187]
	v_add_f32_e32 v70, v68, v69
	v_add_f32_e32 v71, v62, v63
	v_add_f32_e32 v68, v66, v67
	v_add_f32_e32 v69, v64, v65
	v_pk_add_f32 v[194:195], v[70:71], v[68:69]
	v_add_f32_e32 v62, v195, v194
	v_cmp_ngt_f32_e32 vcc, s65, v62
	s_cbranch_vccz .LBB0_1416
	ds_read_b128 v[62:65], v3
	ds_read_b128 v[66:69], v3 offset:64
	ds_read_b128 v[70:73], v3 offset:4352
	ds_read_b128 v[74:77], v3 offset:4416
	ds_read_b128 v[78:81], v3 offset:8704
	ds_read_b128 v[82:85], v3 offset:8768
	ds_read_b128 v[86:89], v3 offset:13056
	ds_read_b128 v[90:93], v3 offset:13120
	v_add3_u32 v246, s28, v208, v209
	s_waitcnt lgkmcnt(7)
	v_mfma_f32_16x16x32_bf16 v[62:65], v[62:65], v[38:41], v[46:49]
	s_waitcnt lgkmcnt(6)
	v_mfma_f32_16x16x32_bf16 v[66:69], v[66:69], v[42:45], v[46:49]
	s_waitcnt lgkmcnt(5)
	v_mfma_f32_16x16x32_bf16 v[70:73], v[70:73], v[38:41], v[50:53]
	s_waitcnt lgkmcnt(4)
	v_mfma_f32_16x16x32_bf16 v[74:77], v[74:77], v[42:45], v[50:53]
	s_waitcnt lgkmcnt(3)
	v_mfma_f32_16x16x32_bf16 v[78:81], v[78:81], v[38:41], v[54:57]
	s_waitcnt lgkmcnt(2)
	v_mfma_f32_16x16x32_bf16 v[82:85], v[82:85], v[42:45], v[54:57]
	s_waitcnt lgkmcnt(1)
	v_mfma_f32_16x16x32_bf16 v[86:89], v[86:89], v[38:41], v[58:61]
	s_waitcnt lgkmcnt(0)
	v_mfma_f32_16x16x32_bf16 v[90:93], v[90:93], v[42:45], v[58:61]
	v_max3_f32 v94, v62, v66, s60
	v_max3_f32 v94, v94, v63, v67
	v_max3_f32 v94, v94, v64, v68
	v_max3_f32 v94, v94, v65, v69
	v_max3_f32 v94, v94, v70, v74
	v_max3_f32 v94, v94, v71, v75
	v_max3_f32 v94, v94, v72, v76
	v_max3_f32 v94, v94, v73, v77
	v_max3_f32 v94, v94, v78, v82
	v_max3_f32 v94, v94, v79, v83
	v_max3_f32 v94, v94, v80, v84
	v_max3_f32 v94, v94, v81, v85
	v_max3_f32 v94, v94, v86, v90
	v_max3_f32 v94, v94, v87, v91
	v_max3_f32 v94, v94, v88, v92
	v_max3_f32 v94, v94, v89, v93
	v_and_b32_e32 v96, 64, v198
	v_mov_b32_e32 v95, v94
	v_mov_b32_e32 v255, v94
	s_nop 1
	v_permlane16_swap_b32_e32 v95, v255
	s_waitcnt lgkmcnt(0)
	v_max_f32_e32 v94, v95, v255
	v_mov_b32_e32 v95, v94
	v_mov_b32_e32 v255, v94
	s_nop 1
	v_permlane32_swap_b32_e32 v95, v255
	s_waitcnt lgkmcnt(0)
; #define LAS __attribute__((address_space(3)))
; DI float fast_exp2(float x) { return __builtin_amdgcn_exp2f(x); }
; #define MFMA16(a, b, c) __builtin_amdgcn_mfma_f32_16x16x32_bf16((a), (b), (c), 0, 0, 0)
; DI u32x2 tr4(const LAS unsigned char* p) { return __builtin_bit_cast(u32x2, __builtin_amdgcn_ds_read_tr16_b64_v4i16((LAS v4i16_t*)p)); }
; DI void at_pv(AtState& S, const f32x4 (&s1)[4], const f32x4 (&s2)[4], float alpha, float ps1, float ps2, const LAS unsigned char* buf, int hh, int fq, int tq, int tp) {
;     S.l1 = S.l1 * alpha + ps1; S.l2 = S.l2 * alpha + ps2;
; #pragma unroll
;     for (int dt = 0; dt < 4; ++dt) { S.O1[dt] = S.O1[dt] * alpha; S.O2[dt] = S.O2[dt] * alpha; }
;     bf16x8 p1[2], p2[2];
; #pragma unroll
;     for (int s = 0; s < 2; ++s) { p1[s] = packp(s1[2 * s], s1[2 * s + 1]); p2[s] = packp(s2[2 * s], s2[2 * s + 1]); }
; #pragma unroll
;     for (int dh = 0; dh < 2; ++dh) {
;         bf16x8 vt[2][2];
; #pragma unroll
;         for (int d2 = 0; d2 < 2; ++d2)
; #pragma unroll
;             for (int s = 0; s < 2; ++s) { const int dt = 2 * dh + d2; const LAS unsigned char* vr = buf + AT_V + (32 * s + 4 * fq + tq) * 288 + (hh * 64 + 16 * dt + 4 * tp) * 2; vt[d2][s] = cat44(tr4(vr), tr4(vr + 16 * 288)); }
;         __builtin_amdgcn_s_setprio(1);
; #pragma unroll
;         for (int s = 0; s < 2; ++s)
; #pragma unroll
;             for (int d2 = 0; d2 < 2; ++d2) { const int dt = 2 * dh + d2; S.O1[dt] = MFMA16(vt[d2][s], p1[s], S.O1[dt]); S.O2[dt] = MFMA16(vt[d2][s], p2[s], S.O2[dt]); }
;         __builtin_amdgcn_s_setprio(0);
;         __builtin_amdgcn_sched_barrier(0);
;     }
; }
; template <int VAR>
; DI void attn_tile(AtState& S, const LAS unsigned char* buf, const bf16x8 q1, const bf16x8 q2, int kt, bool diag, int qpos0, int qpos_l, float slope2, float adv, float decay, int hh, int fr, int fq) {
;     ...
;             lm = fmaxf(lm, __shfl_xor(lm, 16)); lm = fmaxf(lm, __shfl_xor(lm, 32));
;             const float bump = fmaxf(lm, 0.f);
;             const float alpha = decay * fast_exp2(-bump); S.ref += bump;
; #pragma unroll
;             for (int k4 = 0; k4 < 4; ++k4) { s1[k4] = s1[k4] - bump; s2[k4] = s2[k4] - bump; S.cinit[k4] = S.cinit[k4] - bump; }
;             at_exp(s1, s2, ps1, ps2);
;             at_pv(S, s1, s2, alpha, ps1, ps2, buf, hh, fq, tq, tp);
	v_max3_f32 v94, v255, v95, 0
	v_sub_f32_e32 v96, v65, v94
	v_sub_f32_e32 v97, v64, v94
	v_sub_f32_e32 v98, v63, v94
	v_sub_f32_e32 v99, v62, v94
	v_sub_f32_e32 v69, v69, v94
	v_sub_f32_e32 v68, v68, v94
	v_sub_f32_e32 v67, v67, v94
	v_sub_f32_e32 v66, v66, v94
	v_sub_f32_e32 v100, v73, v94
	v_sub_f32_e32 v101, v72, v94
	v_sub_f32_e32 v102, v71, v94
	v_sub_f32_e32 v103, v70, v94
	v_sub_f32_e32 v104, v77, v94
	v_sub_f32_e32 v105, v76, v94
	v_sub_f32_e32 v107, v75, v94
	v_sub_f32_e32 v108, v74, v94
	v_exp_f32_e32 v214, v99
	v_exp_f32_e32 v218, v66
	v_exp_f32_e32 v215, v98
	v_exp_f32_e32 v219, v67
	v_exp_f32_e32 v216, v97
	v_exp_f32_e32 v220, v68
	v_exp_f32_e32 v217, v96
	v_exp_f32_e32 v221, v69
	v_sub_f32_e32 v109, v81, v94
	v_sub_f32_e32 v158, v80, v94
	v_sub_f32_e32 v159, v79, v94
	v_sub_f32_e32 v230, v78, v94
	v_sub_f32_e32 v85, v85, v94
	v_sub_f32_e32 v84, v84, v94
	v_sub_f32_e32 v83, v83, v94
	v_sub_f32_e32 v82, v82, v94
	v_exp_f32_e32 v222, v103
	v_exp_f32_e32 v224, v108
	v_exp_f32_e32 v223, v102
	v_exp_f32_e32 v225, v107
	v_exp_f32_e32 v226, v101
	v_exp_f32_e32 v228, v105
	v_exp_f32_e32 v227, v100
	v_exp_f32_e32 v229, v104
	v_sub_f32_e32 v89, v89, v94
	v_sub_f32_e32 v88, v88, v94
	v_sub_f32_e32 v87, v87, v94
	v_sub_f32_e32 v86, v86, v94
	v_sub_f32_e32 v245, v93, v94
	v_sub_f32_e32 v243, v92, v94
	v_sub_f32_e32 v241, v91, v94
	v_sub_f32_e32 v239, v90, v94
	v_exp_f32_e32 v230, v230
	v_exp_f32_e32 v232, v82
	v_exp_f32_e32 v231, v159
	v_exp_f32_e32 v233, v83
	v_exp_f32_e32 v234, v158
	v_exp_f32_e32 v236, v84
	v_exp_f32_e32 v235, v109
	v_exp_f32_e32 v237, v85
	v_exp_f32_e32 v238, v86
	v_exp_f32_e32 v240, v239
	v_exp_f32_e32 v239, v87
	v_exp_f32_e32 v241, v241
	v_exp_f32_e32 v242, v88
	v_exp_f32_e32 v244, v243
	v_exp_f32_e32 v243, v89
	v_exp_f32_e32 v245, v245
	v_pk_add_f32 v[68:69], v[226:227], v[216:217]
	v_pk_add_f32 v[66:67], v[222:223], v[214:215]
	v_pk_add_f32 v[72:73], v[228:229], v[220:221]
	v_pk_add_f32 v[70:71], v[224:225], v[218:219]
	v_pk_add_f32 v[66:67], v[230:231], v[66:67]
	v_pk_add_f32 v[68:69], v[234:235], v[68:69]
	v_pk_add_f32 v[70:71], v[232:233], v[70:71]
	v_pk_add_f32 v[72:73], v[236:237], v[72:73]
	v_pk_add_f32 v[68:69], v[242:243], v[68:69]
	v_pk_add_f32 v[66:67], v[238:239], v[66:67]
	v_pk_add_f32 v[72:73], v[244:245], v[72:73]
	v_pk_add_f32 v[70:71], v[240:241], v[70:71]
	v_cvt_pk_bf16_f32 v214, v214, v215
	v_cvt_pk_bf16_f32 v215, v216, v217
	v_cvt_pk_bf16_f32 v216, v222, v223
	v_cvt_pk_bf16_f32 v217, v226, v227
	v_cvt_pk_bf16_f32 v218, v218, v219
	v_cvt_pk_bf16_f32 v219, v220, v221
	v_cvt_pk_bf16_f32 v220, v224, v225
	v_cvt_pk_bf16_f32 v221, v228, v229
	v_cvt_pk_bf16_f32 v222, v230, v231
	v_cvt_pk_bf16_f32 v223, v234, v235
	v_cvt_pk_bf16_f32 v224, v238, v239
	v_cvt_pk_bf16_f32 v225, v242, v243
	v_cvt_pk_bf16_f32 v226, v232, v233
	v_cvt_pk_bf16_f32 v227, v236, v237
	v_cvt_pk_bf16_f32 v228, v240, v241
	v_cvt_pk_bf16_f32 v229, v244, v245
	ds_read_b64_tr_b16 v[230:231], v246 offset:17408
	ds_read_b64_tr_b16 v[234:235], v246 offset:17440
	ds_read_b64_tr_b16 v[232:233], v246 offset:22016
	ds_read_b64_tr_b16 v[238:239], v246 offset:26624
	ds_read_b64_tr_b16 v[240:241], v246 offset:31232
	ds_read_b64_tr_b16 v[236:237], v246 offset:22048
	ds_read_b64_tr_b16 v[242:243], v246 offset:26656
	ds_read_b64_tr_b16 v[244:245], v246 offset:31264
	v_exp_f32_e64 v95, -v94
	v_mov_b32_e32 v82, v70
	v_mov_b32_e32 v83, v66
	v_mov_b32_e32 v66, v71
	v_mov_b32_e32 v70, v72
	v_mov_b32_e32 v71, v68
	v_mov_b32_e32 v68, v73
	v_pk_add_f32 v[66:67], v[82:83], v[66:67]
	v_pk_add_f32 v[68:69], v[70:71], v[68:69]
	v_mul_f32_e32 v106, v116, v95
	v_pk_add_f32 v[66:67], v[66:67], v[68:69]
	v_add_f32_e32 v117, v213, v94
	v_sub_f32_e32 v65, v49, v94
	v_sub_f32_e32 v64, v48, v94
	v_sub_f32_e32 v63, v47, v94
	v_sub_f32_e32 v62, v46, v94
	v_sub_f32_e32 v77, v53, v94
	v_sub_f32_e32 v76, v52, v94
	v_sub_f32_e32 v75, v51, v94
	v_sub_f32_e32 v74, v50, v94
	v_sub_f32_e32 v81, v57, v94
	v_sub_f32_e32 v80, v56, v94
	v_sub_f32_e32 v79, v55, v94
	v_sub_f32_e32 v78, v54, v94
	v_sub_f32_e32 v93, v61, v94
	v_sub_f32_e32 v92, v60, v94
	v_sub_f32_e32 v91, v59, v94
	v_sub_f32_e32 v90, v58, v94
	v_pk_fma_f32 v[158:159], v[156:157], v[106:107], v[66:67] op_sel_hi:[1,0,1]
	v_pk_mul_f32 v[68:69], v[154:155], v[106:107] op_sel_hi:[1,0]
	v_pk_mul_f32 v[66:67], v[152:153], v[106:107] op_sel_hi:[1,0]
	v_pk_mul_f32 v[72:73], v[150:151], v[106:107] op_sel_hi:[1,0]
	v_pk_mul_f32 v[70:71], v[148:149], v[106:107] op_sel_hi:[1,0]
	v_pk_mul_f32 v[84:85], v[146:147], v[106:107] op_sel_hi:[1,0]
	v_pk_mul_f32 v[82:83], v[144:145], v[106:107] op_sel_hi:[1,0]
	v_pk_mul_f32 v[88:89], v[138:139], v[106:107] op_sel_hi:[1,0]
	v_pk_mul_f32 v[86:87], v[136:137], v[106:107] op_sel_hi:[1,0]
	v_pk_mul_f32 v[96:97], v[134:135], v[106:107] op_sel_hi:[1,0]
	v_pk_mul_f32 v[94:95], v[132:133], v[106:107] op_sel_hi:[1,0]
	v_pk_mul_f32 v[100:101], v[130:131], v[106:107] op_sel_hi:[1,0]
	v_pk_mul_f32 v[98:99], v[128:129], v[106:107] op_sel_hi:[1,0]
	v_pk_mul_f32 v[104:105], v[126:127], v[106:107] op_sel_hi:[1,0]
	v_pk_mul_f32 v[102:103], v[124:125], v[106:107] op_sel_hi:[1,0]
	v_pk_mul_f32 v[108:109], v[4:5], v[106:107] op_sel_hi:[1,0]
	v_pk_mul_f32 v[106:107], v[122:123], v[106:107] op_sel_hi:[1,0]
	s_setprio 1
	s_waitcnt lgkmcnt(5)
	v_mfma_f32_16x16x32_bf16 v[66:69], v[230:233], v[214:217], v[66:69]
	v_mfma_f32_16x16x32_bf16 v[70:73], v[230:233], v[218:221], v[70:73]
	s_waitcnt lgkmcnt(2)
	v_mfma_f32_16x16x32_bf16 v[82:85], v[234:237], v[214:217], v[82:85]
	v_mfma_f32_16x16x32_bf16 v[230:233], v[234:237], v[218:221], v[86:89]
	v_mfma_f32_16x16x32_bf16 v[66:69], v[238:241], v[222:225], v[66:69]
	v_mfma_f32_16x16x32_bf16 v[86:89], v[238:241], v[226:229], v[70:73]
	s_waitcnt lgkmcnt(0)
	v_mfma_f32_16x16x32_bf16 v[70:73], v[242:245], v[222:225], v[82:85]
	v_mfma_f32_16x16x32_bf16 v[82:85], v[242:245], v[226:229], v[230:233]
	s_setprio 0
	s_nop 1
	ds_read_b64_tr_b16 v[230:231], v246 offset:17472
	ds_read_b64_tr_b16 v[234:235], v246 offset:17504
	ds_read_b64_tr_b16 v[232:233], v246 offset:22080
	ds_read_b64_tr_b16 v[236:237], v246 offset:22112
	ds_read_b64_tr_b16 v[238:239], v246 offset:26688
	ds_read_b64_tr_b16 v[240:241], v246 offset:31296
	ds_read_b64_tr_b16 v[244:245], v246 offset:31328
	ds_read_b64_tr_b16 v[242:243], v246 offset:26720
	s_setprio 1
	s_waitcnt lgkmcnt(5)
	v_mfma_f32_16x16x32_bf16 v[94:97], v[230:233], v[214:217], v[94:97]
	v_mfma_f32_16x16x32_bf16 v[98:101], v[230:233], v[218:221], v[98:101]
	s_waitcnt lgkmcnt(4)
	v_mfma_f32_16x16x32_bf16 v[102:105], v[234:237], v[214:217], v[102:105]
	v_mfma_f32_16x16x32_bf16 v[214:217], v[234:237], v[218:221], v[106:109]
	s_waitcnt lgkmcnt(2)
	v_mfma_f32_16x16x32_bf16 v[94:97], v[238:241], v[222:225], v[94:97]
	v_mfma_f32_16x16x32_bf16 v[106:109], v[238:241], v[226:229], v[98:101]
	s_waitcnt lgkmcnt(0)
	v_mfma_f32_16x16x32_bf16 v[98:101], v[242:245], v[222:225], v[102:105]
	v_mfma_f32_16x16x32_bf16 v[102:105], v[242:245], v[226:229], v[214:217]
	s_setprio 0
	s_cbranch_execnz .LBB0_1409
